# direct HBM->LDS (LDS-DMA) staging of pool weights instead of load/wait/ds_write loop, on sg dword-store + non-GEMM latency stack
# baseline (speedup 1.0000x reference)
; #define LAS __attribute__((address_space(3)))
; __global__ void __launch_bounds__(512, 2) __attribute__((amdgpu_waves_per_eu(2, 2))) mk_fwd(Args a_) {
;     ...
;                 {
;                     const u32x4* srcw = (const u32x4*)(ws + WS_POOLWT + (size_t)l * 4 * 64 * 72 * 2);
;                     for (int i = tid; i < 4 * 64 * 72 * 2 / 16; i += 512) ((LAS u32x4*)(lds + 65536))[i] = srcw[i];
;                     __syncthreads();
;                 }
;     ...
;                 for (int rr = 0; rr < (PROBE_TM == 2 ? 3 : 1); ++rr)
;                 for (int it = vcu; it < MTOK / 64; it += G) pool_item(l, it, lds, PLB, YC, a.in[14], a.in[15], tid, lane, wave);
.LBB0_82:
	v_readfirstlane_b32 s3, v156
	s_nop 1
	v_readfirstlane_b32 s2, v3
	s_nop 3
	s_mov_b32 m0, s2
	s_nop 0
	global_load_lds_dwordx4 v[0:1], off
	v_lshl_add_u64 v[0:1], v[0:1], 0, s[6:7]
	s_add_i32 s2, s2, 0x2000
	s_mov_b32 m0, s2
	s_nop 0
	global_load_lds_dwordx4 v[0:1], off
	v_lshl_add_u64 v[0:1], v[0:1], 0, s[6:7]
	s_add_i32 s2, s2, 0x2000
	s_mov_b32 m0, s2
	s_nop 0
	global_load_lds_dwordx4 v[0:1], off
	v_lshl_add_u64 v[0:1], v[0:1], 0, s[6:7]
	s_add_i32 s2, s2, 0x2000
	s_mov_b32 m0, s2
	s_nop 0
	global_load_lds_dwordx4 v[0:1], off
	s_cmp_lt_u32 s3, 0x100
	s_cbranch_scc0 .Lpw_skip
	v_lshl_add_u64 v[0:1], v[0:1], 0, s[6:7]
	s_add_i32 s2, s2, 0x2000
	s_mov_b32 m0, s2
	s_nop 0
	global_load_lds_dwordx4 v[0:1], off
.Lpw_skip:
.LBB0_83:
	s_or_b64 exec, exec, s[0:1]
	v_writelane_b32 v253, s66, 34
	v_writelane_b32 v253, s65, 35
	v_writelane_b32 v253, s64, 36
	v_and_b32_e32 v35, 0xff, v156
	v_lshlrev_b32_e32 v33, 1, v35
	v_writelane_b32 v253, s65, 37
	v_lshlrev_b32_e32 v32, 3, v158
	v_readlane_b32 s0, v253, 15
	v_readlane_b32 s1, v253, 16
	s_cmpk_lt_i32 s0, 0x200
	s_cselect_b64 s[0:1], -1, 0
	v_writelane_b32 v253, s0, 38
	s_and_b64 vcc, exec, s[0:1]
	v_lshlrev_b32_e32 v34, 1, v159
	v_writelane_b32 v253, s1, 39
	s_waitcnt vmcnt(0)
	s_waitcnt lgkmcnt(0)
	s_barrier
	s_cbranch_vccz .LBB0_99
	v_readlane_b32 s0, v253, 33
	s_or_b32 s6, s0, 24
	s_or_b32 s8, s0, 25
	s_or_b32 s10, s0, 26
	s_or_b32 s12, s0, 27
	s_or_b32 s14, s0, 28
	s_or_b32 s16, s0, 29
	s_or_b32 s18, s0, 30
	s_or_b32 s20, s0, 31
	s_mul_i32 s0, s42, 0x210
	s_add_i32 s1, s0, 0xc60
	v_writelane_b32 v253, s1, 40
	v_writelane_b32 v253, s0, 41
	s_addk_i32 s0, 0x18c0
	v_writelane_b32 v253, s0, 42
	v_or_b32_e32 v0, s42, v159
	s_movk_i32 s0, 0x210
	v_mul_lo_u32 v0, v0, s0
	s_lshl_b32 s0, s41, 1
	s_add_i32 s0, s0, 0
	v_lshlrev_b32_e32 v2, 1, v32
	v_add3_u32 v42, s0, v0, v2
	v_readlane_b32 s0, v253, 22
	v_readlane_b32 s1, v253, 23
	s_load_dwordx2 s[4:5], s[0:1], 0xa8
	s_ashr_i32 s43, s42, 31
	v_readlane_b32 s2, v253, 24
	v_or_b32_e32 v0, 32, v244
	v_readlane_b32 s3, v253, 25
	s_waitcnt lgkmcnt(0)
	s_add_u32 s35, s4, 0x13400000
	s_addc_u32 s34, s5, 0
	s_lshl_b32 s2, s2, 8
	s_load_dwordx2 s[0:1], s[0:1], 0x78
	s_or_b32 s2, s41, s2
	v_or_b32_e32 v4, s41, v0
	v_or_b32_e32 v234, s2, v0
	v_or_b32_e32 v0, s2, v159
	v_readlane_b32 s2, v253, 15
	v_readlane_b32 s3, v253, 16
	s_ashr_i32 s3, s2, 31
	v_mov_b32_e32 v1, v235
	s_lshl_b64 s[28:29], s[2:3], 6
	s_waitcnt lgkmcnt(0)
; __device__ __forceinline__ void pool_item(int l, int it, LAS unsigned char* lds, const bf16_t* PLB, bf16_t* YC, const float* pool_w, const float* pool_scale, int tid, int lane, int wave) {
;     ...
;     const size_t r0 = (size_t)it * 64; const int pos0 = (int)(r0 & (SEQ - 1));
;     {
;         const int c = tid & 255, th = wave >> 2, g = (wave & 3), ts = th * 32;
;         float x[47];
; #pragma unroll
;         for (int ib = 0; ib < 48; ib += 12) {
;             unsigned raw[12]; const void* pp[12];
; #pragma unroll
;             for (int j = 0; j < 12; ++j) { const int off = ts - 15 + (ib + j < 47 ? ib + j : 46); pp[j] = PLB + (r0 + (pos0 + off >= 0 ? off : -pos0)) * BW; }
;             ld_u16_s12(raw, (unsigned)c * 2u, pp);
	v_lshl_add_u64 v[36:37], v[0:1], 2, s[0:1]
	v_lshl_add_u64 v[38:39], v[234:235], 2, s[0:1]
	s_add_u32 s0, s42, s28
	v_mov_b32_e32 v161, v235
	s_addc_u32 s1, s43, s29
	v_lshl_add_u64 v[0:1], s[0:1], 0, v[160:161]
	s_lshl_b32 s0, s40, 1
	v_lshlrev_b64 v[0:1], 9, v[0:1]
	s_and_b32 s0, s0, 0x180
	s_ashr_i32 s97, s96, 31
	v_or3_b32 v0, v0, s0, v34
	s_lshl_b64 s[0:1], s[96:97], 15
	v_writelane_b32 v253, s0, 43
	s_lshl_b32 s3, s2, 6
	v_or_b32_e32 v3, s41, v159
	v_writelane_b32 v253, s1, 44
	s_lshl_b32 s0, s96, 6
	v_writelane_b32 v253, s0, 45
	s_sub_i32 s0, s42, 32
	s_ashr_i32 s1, s0, 31
	s_add_u32 s22, s0, 17
	s_addc_u32 s23, s1, 0
	v_writelane_b32 v253, s22, 46
	v_mul_u32_u24_e32 v3, 0x90, v3
	v_lshl_add_u64 v[0:1], s[4:5], 0, v[0:1]
	v_writelane_b32 v253, s23, 47
	s_lshl_b64 s[22:23], s[96:97], 6
	v_writelane_b32 v253, s22, 48
	v_lshl_add_u32 v43, v35, 1, 0
	s_nop 0
	v_writelane_b32 v253, s23, 49
	s_add_u32 s22, s0, 18
	s_addc_u32 s23, s1, 0
	v_writelane_b32 v253, s22, 50
	s_nop 1
	v_writelane_b32 v253, s23, 51
	s_add_u32 s22, s0, 19
	s_addc_u32 s23, s1, 0
	v_writelane_b32 v253, s22, 52
	s_nop 1
	v_writelane_b32 v253, s23, 53
	s_add_u32 s22, s0, 20
	s_addc_u32 s23, s1, 0
	v_writelane_b32 v253, s22, 54
	s_nop 1
	v_writelane_b32 v253, s23, 55
	s_add_u32 s22, s0, 21
	s_addc_u32 s23, s1, 0
	v_writelane_b32 v253, s22, 56
	s_nop 1
	v_writelane_b32 v253, s23, 57
	s_add_u32 s22, s0, 22
	s_addc_u32 s23, s1, 0
	v_writelane_b32 v253, s22, 58
	s_ashr_i32 s21, s20, 31
	s_ashr_i32 s19, s18, 31
	s_ashr_i32 s17, s16, 31
	s_ashr_i32 s15, s14, 31
	s_ashr_i32 s13, s12, 31
	s_ashr_i32 s11, s10, 31
	s_ashr_i32 s9, s8, 31
	s_ashr_i32 s7, s6, 31
	v_writelane_b32 v253, s23, 59
	s_add_u32 s22, s42, 23
	s_addc_u32 s23, s43, 0
	v_writelane_b32 v253, s22, 60
	s_nop 1
	v_writelane_b32 v253, s23, 61
	s_add_u32 s22, s42, 22
	s_addc_u32 s23, s43, 0
	v_writelane_b32 v253, s22, 62
	s_nop 1
	v_writelane_b32 v253, s23, 63
	s_add_u32 s22, s42, 21
	s_addc_u32 s23, s43, 0
	v_writelane_b32 v255, s22, 0
	s_nop 1
	v_writelane_b32 v255, s23, 1
	s_add_u32 s22, s42, 20
	s_addc_u32 s23, s43, 0
	v_writelane_b32 v255, s22, 2
	s_nop 1
	v_writelane_b32 v255, s23, 3
	s_add_u32 s22, s42, 19
	s_addc_u32 s23, s43, 0
	v_writelane_b32 v255, s22, 4
	s_nop 1
	v_writelane_b32 v255, s23, 5
	s_add_u32 s22, s42, 18
	s_addc_u32 s23, s43, 0
	v_writelane_b32 v255, s22, 6
	s_nop 1
	v_writelane_b32 v255, s23, 7
	s_add_u32 s22, s42, 17
	s_addc_u32 s23, s43, 0
	v_writelane_b32 v255, s22, 8
	s_nop 1
	v_writelane_b32 v255, s23, 9
	s_add_u32 s22, s42, 16
	s_addc_u32 s23, s43, 0
	v_writelane_b32 v255, s22, 10
	s_nop 1
	v_writelane_b32 v255, s23, 11
	s_add_u32 s22, s42, 15
	s_addc_u32 s23, s43, 0
	v_writelane_b32 v255, s22, 12
	s_nop 1
	v_writelane_b32 v255, s23, 13
	s_add_u32 s22, s42, 14
	s_addc_u32 s23, s43, 0
	v_writelane_b32 v255, s22, 14
	s_nop 1
	v_writelane_b32 v255, s23, 15
	s_add_u32 s22, s42, 13
	s_addc_u32 s23, s43, 0
	v_writelane_b32 v255, s22, 16
	s_nop 1
	v_writelane_b32 v255, s23, 17
	s_add_u32 s22, s42, 12
	s_addc_u32 s23, s43, 0
	v_writelane_b32 v255, s22, 18
	s_nop 1
	v_writelane_b32 v255, s23, 19
	s_add_u32 s22, s42, 11
	s_addc_u32 s23, s43, 0
	v_writelane_b32 v255, s22, 20
	s_nop 1
	v_writelane_b32 v255, s23, 21
	s_add_u32 s22, s42, 10
	s_addc_u32 s23, s43, 0
	v_writelane_b32 v255, s22, 22
	s_nop 1
	v_writelane_b32 v255, s23, 23
	s_add_u32 s22, s42, 9
	s_addc_u32 s23, s43, 0
	v_writelane_b32 v255, s22, 24
	s_nop 1
	v_writelane_b32 v255, s23, 25
	s_add_u32 s22, s42, 8
	s_addc_u32 s23, s43, 0
	v_writelane_b32 v255, s22, 26
	s_nop 1
	v_writelane_b32 v255, s23, 27
	s_add_u32 s22, s42, 7
	s_addc_u32 s23, s43, 0
	v_writelane_b32 v255, s22, 28
	s_nop 1
	v_writelane_b32 v255, s23, 29
	s_add_u32 s22, s42, 6
	s_addc_u32 s23, s43, 0
	v_writelane_b32 v255, s22, 30
	s_nop 1
	v_writelane_b32 v255, s23, 31
	s_add_u32 s22, s42, 5
	s_addc_u32 s23, s43, 0
	v_writelane_b32 v255, s22, 32
	s_nop 1
	v_writelane_b32 v255, s23, 33
	s_add_u32 s22, s42, 4
	s_addc_u32 s23, s43, 0
	v_writelane_b32 v255, s22, 34
	s_nop 1
	v_writelane_b32 v255, s23, 35
	s_add_u32 s22, s42, 3
	s_addc_u32 s23, s43, 0
	v_writelane_b32 v255, s22, 36
	s_nop 1
	v_writelane_b32 v255, s23, 37
	s_add_u32 s22, s42, 2
	s_addc_u32 s23, s43, 0
	v_writelane_b32 v255, s22, 38
	s_nop 1
	v_writelane_b32 v255, s23, 39
	s_add_u32 s22, s42, 1
	s_addc_u32 s23, s43, 0
	v_writelane_b32 v255, s22, 40
	s_nop 1
	v_writelane_b32 v255, s23, 41
	s_add_u32 s22, s0, 31
	s_addc_u32 s23, s1, 0
	v_writelane_b32 v255, s22, 42
	s_nop 1
	v_writelane_b32 v255, s23, 43
	s_add_u32 s22, s0, 30
	s_addc_u32 s23, s1, 0
	v_writelane_b32 v255, s22, 44
	s_nop 1
	v_writelane_b32 v255, s23, 45
	s_add_u32 s22, s0, 29
	s_addc_u32 s23, s1, 0
	v_writelane_b32 v255, s22, 46
	s_nop 1
	v_writelane_b32 v255, s23, 47
	s_add_u32 s22, s0, 28
	s_addc_u32 s23, s1, 0
	v_writelane_b32 v255, s22, 48
	s_nop 1
	v_writelane_b32 v255, s23, 49
	s_add_u32 s22, s0, 27
	s_addc_u32 s23, s1, 0
	v_writelane_b32 v255, s22, 50
	s_nop 1
	v_writelane_b32 v255, s23, 51
	s_add_u32 s22, s0, 26
	s_addc_u32 s23, s1, 0
	v_writelane_b32 v255, s22, 52
	s_nop 1
	v_writelane_b32 v255, s23, 53
	s_add_u32 s22, s0, 25
	s_addc_u32 s23, s1, 0
	v_writelane_b32 v255, s22, 54
	s_nop 1
	v_writelane_b32 v255, s23, 55
	s_add_u32 s22, s0, 24
	s_addc_u32 s23, s1, 0
	v_writelane_b32 v255, s22, 56
	s_add_u32 s0, s0, 23
	s_addc_u32 s1, s1, 0
	v_writelane_b32 v255, s23, 57
	v_writelane_b32 v255, s0, 58
	s_nop 1
	v_writelane_b32 v255, s1, 59
	v_readlane_b32 s0, v253, 3
	v_writelane_b32 v255, s6, 60
	s_nop 0
	v_add3_u32 v44, s0, v3, v2
	v_mul_u32_u24_e32 v3, 0x90, v4
	v_add3_u32 v45, s0, v3, v2
	s_mov_b64 s[0:1], 0xc403640
	v_lshl_add_u64 v[40:41], v[0:1], 0, s[0:1]
	v_writelane_b32 v255, s7, 61
	s_mul_i32 s0, s6, 0x210
	v_writelane_b32 v255, s0, 62
	v_writelane_b32 v255, s8, 63
	s_mul_i32 s0, s8, 0x210
	s_nop 0
	v_writelane_b32 v254, s9, 0
	v_writelane_b32 v254, s0, 1
	v_writelane_b32 v254, s10, 2
	s_mul_i32 s0, s10, 0x210
	s_nop 0
	v_writelane_b32 v254, s11, 3
	v_writelane_b32 v254, s0, 4
	v_writelane_b32 v254, s12, 5
	s_mul_i32 s0, s12, 0x210
	s_nop 0
	v_writelane_b32 v254, s13, 6
	v_writelane_b32 v254, s0, 7
	v_writelane_b32 v254, s14, 8
	s_mul_i32 s0, s14, 0x210
	s_nop 0
	v_writelane_b32 v254, s15, 9
	v_writelane_b32 v254, s0, 10
	v_writelane_b32 v254, s16, 11
	s_mul_i32 s0, s16, 0x210
	s_nop 0
	v_writelane_b32 v254, s17, 12
	v_writelane_b32 v254, s0, 13
	v_writelane_b32 v254, s18, 14
	s_mul_i32 s0, s18, 0x210
	s_nop 0
	v_writelane_b32 v254, s19, 15
	v_writelane_b32 v254, s0, 16
	v_writelane_b32 v254, s20, 17
	s_mul_i32 s0, s20, 0x210
	s_nop 0
	v_writelane_b32 v254, s21, 18
	v_writelane_b32 v254, s0, 19
	s_mov_b32 s0, s2
	v_writelane_b32 v253, s0, 15
	v_writelane_b32 v254, s96, 20
	s_mov_b64 s[20:21], 0
	v_writelane_b32 v253, s1, 16
	v_writelane_b32 v254, s97, 21
	s_branch .LBB0_87
